# SB main loop edge: all-done ballot evaluated at the loop tail (flag reads overlap the sub-tile work) + done flag taken from SCC instead of cndmask/readfirstlane
# baseline (speedup 1.0000x reference)
; #define MFMA32(a, b, c) __builtin_amdgcn_mfma_f32_32x32x16_bf16((a), (b), (c), 0, 0, 0)
; DI void sb_block2(const Params& p, LAS unsigned char* lds, int bh, int qb2, int tid) {
;     ...
;                             for (int s2 = 0; s2 < 2; ++s2) { o0[g] = MFMA32(vf[s2], pf[s2], o0[g]); o1[g] = MFMA32(vf[2 + s2], pf[s2], o1[g]); }
;                             if (__all(carry[g] < SB_PTHR)) done[g] = true;
.Lsb_join_1:
	v_cmp_gt_f32_e32 vcc, s68, v191
	v_mfma_f32_32x32x16_bf16 v[82:97], v[42:45], v[0:3], 0
	v_mul_f32_e32 v2, v17, v4
	v_mul_f32_e32 v3, v18, v4
	v_pk_mul_f32 v[4:5], v[14:15], v[4:5] op_sel_hi:[1,0]
	v_cvt_pk_bf16_f32 v0, v6, v7
	v_cvt_pk_bf16_f32 v1, v8, v9
	v_cvt_pk_bf16_f32 v2, v2, v3
	v_cvt_pk_bf16_f32 v3, v4, v5
	s_cmp_eq_u64 vcc, exec
	s_cselect_b64 s[0:1], -1, 0
	s_cselect_b32 s81, 1, 0
	v_mfma_f32_32x32x16_bf16 v[98:113], v[38:41], v[0:3], v[98:113]
	v_mfma_f32_32x32x16_bf16 v[82:97], v[34:37], v[0:3], v[82:97]

; #define MFMA32(a, b, c) __builtin_amdgcn_mfma_f32_32x32x16_bf16((a), (b), (c), 0, 0, 0)
; DI void sb_block2(const Params& p, LAS unsigned char* lds, int bh, int qb2, int tid) {
;     ...
;                             for (int s2 = 0; s2 < 2; ++s2) { o0[g] = MFMA32(vf[s2], pf[s2], o0[g]); o1[g] = MFMA32(vf[2 + s2], pf[s2], o1[g]); }
;                             if (__all(carry[g] < SB_PTHR)) done[g] = true;
.Lsb_join_2:
	v_cmp_gt_f32_e32 vcc, s68, v191
	s_cmp_eq_u64 vcc, exec
	s_cselect_b64 s[0:1], -1, 0
	s_cselect_b32 s81, 1, 0
	v_mfma_f32_32x32x16_bf16 v[82:97], v[146:149], v[0:3], v[82:97]

; #define LAS __attribute__((address_space(3)))
; #define SB_WAITV(n) asm volatile("s_waitcnt vmcnt(" #n ") lgkmcnt(0)" ::: "memory")
; #define SB_WAITV(n) asm volatile("s_waitcnt vmcnt(" #n ") lgkmcnt(0)" ::: "memory")
; DI void sb_block2(const Params& p, LAS unsigned char* lds, int bh, int qb2, int tid) {
;     ...
;         if (lane == 0) flags[(it & 1) * 8 + wu] = (done[0] && done[1]) ? 1 : 0;
;         int lowest = ktop - (SB_NB - 1) - (it > 0 ? it - 1 : 0); if (lowest < 0) lowest = 0;
;         int ahead = kt - lowest; if (ahead < 0) ahead = 0;
;         if (wu < 2) { switch (ahead) { case 0: SB_WAITV(0); break; case 1: SB_WAITV(3); break; case 2: SB_WAITV(6); break; case 3: SB_WAITV(9); break; case 4: SB_WAITV(12); break; case 5: SB_WAITV(15); break; default: SB_WAITV(18); break; } }
;         else { switch (ahead) { case 0: SB_WAITV(0); break; case 1: SB_WAITV(2); break; case 2: SB_WAITV(4); break; case 3: SB_WAITV(6); break; case 4: SB_WAITV(8); break; case 5: SB_WAITV(10); break; default: SB_WAITV(12); break; } }
;         __builtin_amdgcn_s_barrier();
;         asm volatile("" ::: "memory");
;         {
;             const LAS int* f = flags + (it & 1) * 8;
;             const int all = f[0] & f[1] & f[2] & f[3] & f[4] & f[5] & f[6] & f[7];
;             if (__builtin_amdgcn_readfirstlane(all)) break;
;         }
;     ...
;             if (kt == 0) { done[0] = true; done[1] = true; }
;         }
;         cur = cur == SB_NB - 1 ? 0 : cur + 1;
.LBB0_850:
	s_waitcnt lgkmcnt(0)
	v_and_b32_e32 v230, v231, v230
	v_and_b32_e32 v230, v230, v232
	v_and_b32_e32 v230, v230, v233
	v_and_b32_e32 v230, v230, v234
	v_and_b32_e32 v230, v230, v235
	v_and_b32_e32 v230, v230, v236
	v_and_b32_e32 v230, v230, v237
	s_nop 0
	v_readfirstlane_b32 s0, v230
	s_cmp_lg_u32 s0, 0
	s_cbranch_scc1 .LBB0_803
	v_sub_co_u32_e64 v0, s[0:1], s54, 1
	s_and_b64 s[2:3], s[0:1], exec
	s_cselect_b32 s81, 1, s81
	s_or_b64 s[62:63], s[0:1], s[62:63]
	s_add_i32 s0, s75, 1
	s_cmp_lg_u32 s75, 6
	v_readfirstlane_b32 s54, v0
	s_cselect_b32 s75, s0, 0
	s_sub_i32 s79, s79, 64
	s_add_i32 s78, s78, -1
	s_add_i32 s80, s80, 8

; #define LAS __attribute__((address_space(3)))
; #define SB_WAITV(n) asm volatile("s_waitcnt vmcnt(" #n ") lgkmcnt(0)" ::: "memory")
; #define SB_WAITV(n) asm volatile("s_waitcnt vmcnt(" #n ") lgkmcnt(0)" ::: "memory")
; DI void sb_block2(const Params& p, LAS unsigned char* lds, int bh, int qb2, int tid) {
;     ...
;         if (lane == 0) flags[(it & 1) * 8 + wu] = (done[0] && done[1]) ? 1 : 0;
;         int lowest = ktop - (SB_NB - 1) - (it > 0 ? it - 1 : 0); if (lowest < 0) lowest = 0;
;         int ahead = kt - lowest; if (ahead < 0) ahead = 0;
;         if (wu < 2) { switch (ahead) { case 0: SB_WAITV(0); break; case 1: SB_WAITV(3); break; case 2: SB_WAITV(6); break; case 3: SB_WAITV(9); break; case 4: SB_WAITV(12); break; case 5: SB_WAITV(15); break; default: SB_WAITV(18); break; } }
;         else { switch (ahead) { case 0: SB_WAITV(0); break; case 1: SB_WAITV(2); break; case 2: SB_WAITV(4); break; case 3: SB_WAITV(6); break; case 4: SB_WAITV(8); break; case 5: SB_WAITV(10); break; default: SB_WAITV(12); break; } }
;         __builtin_amdgcn_s_barrier();
;         asm volatile("" ::: "memory");
;         {
;             const LAS int* f = flags + (it & 1) * 8;
;             const int all = f[0] & f[1] & f[2] & f[3] & f[4] & f[5] & f[6] & f[7];
;             if (__builtin_amdgcn_readfirstlane(all)) break;
;         }
.LBB0_902:
	s_and_b32 s0, s80, 8
	s_lshl_b32 s0, s0, 2
	s_add_i32 s0, s0, 0
	s_add_i32 s0, s0, 0x1f800
	s_barrier
	v_mov_b32_e32 v238, s0
	ds_read_b128 v[230:233], v238
	ds_read_b128 v[234:237], v238 offset:16
	s_mov_b64 s[0:1], -1

; DI void sb_block2(const Params& p, LAS unsigned char* lds, int bh, int qb2, int tid) {
;     ...
;                             if (__all(carry[g] < SB_PTHR)) done[g] = true;
.Lsb_join_6:
	v_cmp_gt_f32_e32 vcc, s68, v191
	s_cmp_eq_u64 vcc, exec
	s_cselect_b64 s[0:1], -1, 0
	s_cselect_b32 s81, 1, 0
	v_mfma_f32_32x32x16_bf16 v[82:97], v[146:149], v[0:3], v[82:97]
	s_branch .LBB0_850
